# GEMM k-loops: raised wave priority (s_setprio 2) from the first MFMA of a k-step to its last, back to 0 before the staging barrier
# speedup vs baseline: 1.0088x; 1.0088x over previous
; template <class Epi>
; __device__ __forceinline__ void gemm_tile64(const bf16_t* A, const bf16_t* Bt, int tm, int tn, const Epi& epi, char* smem, const float* ssq, int nparts) {
;     ...
;         for (int ks = 0; ks < 2; ++ks) {
;             bf16x8 af[4], bfr[4];
; #pragma unroll
;             for (int m = 0; m < 4; ++m) { const int r = wr * 64 + m * 16 + fr; af[m] = *(const bf16x8*)(sA + r * 64 + (((ks * 4 + fq) ^ ((r >> 1) & 7)) * 8)); }
; #pragma unroll
;             for (int n = 0; n < 4; ++n) { const int r = wc * 64 + n * 16 + fr; bfr[n] = *(const bf16x8*)(sB + r * 64 + (((ks * 4 + fq) ^ ((r >> 1) & 7)) * 8)); }
; #pragma unroll
;             for (int m = 0; m < 4; ++m)
; #pragma unroll
;                 for (int n = 0; n < 4; ++n) acc[m][n] = __builtin_amdgcn_mfma_f32_16x16x32_bf16(bfr[n], af[m], acc[m][n], 0, 0, 0);
;     __device__ __forceinline__ void operator()(const f32x4 (&acc)[4][4], int tm, int tn, int wr, int wc, int fr, int fq, const float* sRs) const {
;     ...
;         for (int m = 0; m < 4; ++m) {
;             const int rl = wr * 64 + m * 16 + fr;
;             const float rs = sRs[rl];
;             if (tn == 0 && wc == 0 && fq == 0) rstd2[(size_t)tm * 128 + rl] = rs;
.Lgs_nopf:
	s_setprio 2
	s_waitcnt lgkmcnt(3)
	v_mfma_f32_16x16x32_bf16 v[60:63], v[80:83], v[88:91], v[60:63]
	v_mfma_f32_16x16x32_bf16 v[56:59], v[84:87], v[88:91], v[56:59]
	s_waitcnt lgkmcnt(1)
	v_mfma_f32_16x16x32_bf16 v[52:55], v[116:119], v[88:91], v[52:55]
	s_waitcnt lgkmcnt(0)
	v_mfma_f32_16x16x32_bf16 v[48:51], v[120:123], v[88:91], v[48:51]
	v_mfma_f32_16x16x32_bf16 v[44:47], v[80:83], v[92:95], v[44:47]
	v_mfma_f32_16x16x32_bf16 v[40:43], v[84:87], v[92:95], v[40:43]
	v_mfma_f32_16x16x32_bf16 v[36:39], v[116:119], v[92:95], v[36:39]
	v_mfma_f32_16x16x32_bf16 v[32:35], v[120:123], v[92:95], v[32:35]
	ds_read_b128 v[88:91], v108 offset:4096
	ds_read_b128 v[92:95], v108 offset:6144
	s_waitcnt lgkmcnt(1)
	v_mfma_f32_16x16x32_bf16 v[28:31], v[80:83], v[88:91], v[28:31]
	v_mfma_f32_16x16x32_bf16 v[24:27], v[84:87], v[88:91], v[24:27]
	v_mfma_f32_16x16x32_bf16 v[20:23], v[116:119], v[88:91], v[20:23]
	v_mfma_f32_16x16x32_bf16 v[12:15], v[120:123], v[88:91], v[12:15]
	s_waitcnt lgkmcnt(0)
	v_mfma_f32_16x16x32_bf16 v[0:3], v[80:83], v[92:95], v[0:3]
	v_mfma_f32_16x16x32_bf16 v[16:19], v[84:87], v[92:95], v[16:19]
	ds_read_b128 v[80:83], v111 offset:16384
	ds_read_b128 v[84:87], v111 offset:18432
	v_mfma_f32_16x16x32_bf16 v[8:11], v[116:119], v[92:95], v[8:11]
	v_mfma_f32_16x16x32_bf16 v[4:7], v[120:123], v[92:95], v[4:7]
	ds_read_b128 v[88:91], v110
	ds_read_b128 v[92:95], v110 offset:2048
	ds_read_b128 v[116:119], v111 offset:20480
	ds_read_b128 v[120:123], v111 offset:22528
	s_waitcnt lgkmcnt(3)
	v_mfma_f32_16x16x32_bf16 v[60:63], v[80:83], v[88:91], v[60:63]
	v_mfma_f32_16x16x32_bf16 v[56:59], v[84:87], v[88:91], v[56:59]
	s_waitcnt lgkmcnt(1)
	v_mfma_f32_16x16x32_bf16 v[52:55], v[116:119], v[88:91], v[52:55]
	s_waitcnt lgkmcnt(0)
	v_mfma_f32_16x16x32_bf16 v[48:51], v[120:123], v[88:91], v[48:51]
	ds_read_b128 v[88:91], v110 offset:4096
	ds_read_b128 v[144:147], v110 offset:6144
	v_mfma_f32_16x16x32_bf16 v[44:47], v[80:83], v[92:95], v[44:47]
	v_mfma_f32_16x16x32_bf16 v[40:43], v[84:87], v[92:95], v[40:43]
	v_mfma_f32_16x16x32_bf16 v[36:39], v[116:119], v[92:95], v[36:39]
	v_mfma_f32_16x16x32_bf16 v[32:35], v[120:123], v[92:95], v[32:35]
	s_waitcnt lgkmcnt(1)
	v_mfma_f32_16x16x32_bf16 v[28:31], v[80:83], v[88:91], v[28:31]
	v_mfma_f32_16x16x32_bf16 v[24:27], v[84:87], v[88:91], v[24:27]
	v_mfma_f32_16x16x32_bf16 v[20:23], v[116:119], v[88:91], v[20:23]
	v_mfma_f32_16x16x32_bf16 v[12:15], v[120:123], v[88:91], v[12:15]
	s_waitcnt lgkmcnt(0)
	v_mfma_f32_16x16x32_bf16 v[0:3], v[80:83], v[144:147], v[0:3]
	v_mfma_f32_16x16x32_bf16 v[16:19], v[84:87], v[144:147], v[16:19]
	v_mfma_f32_16x16x32_bf16 v[8:11], v[116:119], v[144:147], v[8:11]
	v_mfma_f32_16x16x32_bf16 v[4:7], v[120:123], v[144:147], v[4:7]
	s_setprio 0
	s_cmp_eq_u32 s13, 17
	s_cbranch_scc0 .LBB0_51
	s_mov_b32 s21, 0
	s_movk_i32 s20, 0x780
	s_mov_b32 s14, 15
	v_lshl_or_b32 v64, v97, 6, v96
	v_lshlrev_b32_e32 v67, 2, v64
	ds_read_b32 v66, v67 offset:32768
	v_or3_b32 v65, v98, s22, v99
	v_cmp_eq_u32_e32 vcc, 0, v65
	s_lshl_b32 s13, s12, 9
	v_ashrrev_i32_e32 v65, 31, v64
	s_and_saveexec_b64 s[24:25], vcc
	s_cbranch_execz .LBB0_54
	v_readlane_b32 s36, v165, 42
	v_readlane_b32 s40, v165, 46
	v_readlane_b32 s41, v165, 47
	s_add_u32 s14, s40, s13
	s_addc_u32 s15, s41, 0
	v_lshl_add_u64 v[68:69], v[64:65], 2, s[14:15]
	v_readlane_b32 s37, v165, 43
	v_readlane_b32 s38, v165, 44
	v_readlane_b32 s39, v165, 45
	v_readlane_b32 s42, v165, 48
	v_readlane_b32 s43, v165, 49
	v_readlane_b32 s44, v165, 50
	v_readlane_b32 s45, v165, 51
	v_readlane_b32 s46, v165, 52
	v_readlane_b32 s47, v165, 53
	v_readlane_b32 s48, v165, 54
	v_readlane_b32 s49, v165, 55
	v_readlane_b32 s50, v165, 56
	v_readlane_b32 s51, v165, 57
	s_waitcnt lgkmcnt(0)
	global_store_dword v[68:69], v66, off

; template <class Epi>
; __device__ __forceinline__ void gemm_tile64(const bf16_t* A, const bf16_t* Bt, int tm, int tn, const Epi& epi, char* smem, const float* ssq, int nparts) {
;     ...
;         for (int ks = 0; ks < 2; ++ks) {
;             bf16x8 af[4], bfr[4];
; #pragma unroll
;             for (int m = 0; m < 4; ++m) { const int r = wr * 64 + m * 16 + fr; af[m] = *(const bf16x8*)(sA + r * 64 + (((ks * 4 + fq) ^ ((r >> 1) & 7)) * 8)); }
; #pragma unroll
;             for (int n = 0; n < 4; ++n) { const int r = wc * 64 + n * 16 + fr; bfr[n] = *(const bf16x8*)(sB + r * 64 + (((ks * 4 + fq) ^ ((r >> 1) & 7)) * 8)); }
; #pragma unroll
;             for (int m = 0; m < 4; ++m)
; #pragma unroll
;                 for (int n = 0; n < 4; ++n) acc[m][n] = __builtin_amdgcn_mfma_f32_16x16x32_bf16(bfr[n], af[m], acc[m][n], 0, 0, 0);
.Lgo_nopf:
	s_setprio 2
	s_waitcnt lgkmcnt(3)
	v_mfma_f32_16x16x32_bf16 v[60:63], v[80:83], v[88:91], v[60:63]
	v_mfma_f32_16x16x32_bf16 v[56:59], v[84:87], v[88:91], v[56:59]
	s_waitcnt lgkmcnt(1)
	v_mfma_f32_16x16x32_bf16 v[52:55], v[116:119], v[88:91], v[52:55]
	s_waitcnt lgkmcnt(0)
	v_mfma_f32_16x16x32_bf16 v[48:51], v[120:123], v[88:91], v[48:51]
	v_mfma_f32_16x16x32_bf16 v[44:47], v[80:83], v[92:95], v[44:47]
	v_mfma_f32_16x16x32_bf16 v[40:43], v[84:87], v[92:95], v[40:43]
	v_mfma_f32_16x16x32_bf16 v[36:39], v[116:119], v[92:95], v[36:39]
	v_mfma_f32_16x16x32_bf16 v[32:35], v[120:123], v[92:95], v[32:35]
	ds_read_b128 v[88:91], v108 offset:4096
	ds_read_b128 v[92:95], v108 offset:6144
	s_waitcnt lgkmcnt(1)
	v_mfma_f32_16x16x32_bf16 v[28:31], v[80:83], v[88:91], v[28:31]
	v_mfma_f32_16x16x32_bf16 v[24:27], v[84:87], v[88:91], v[24:27]
	v_mfma_f32_16x16x32_bf16 v[20:23], v[116:119], v[88:91], v[20:23]
	v_mfma_f32_16x16x32_bf16 v[16:19], v[120:123], v[88:91], v[16:19]
	s_waitcnt lgkmcnt(0)
	v_mfma_f32_16x16x32_bf16 v[4:7], v[80:83], v[92:95], v[4:7]
	v_mfma_f32_16x16x32_bf16 v[12:15], v[84:87], v[92:95], v[12:15]
	ds_read_b128 v[80:83], v111 offset:16384
	ds_read_b128 v[84:87], v111 offset:18432
	v_mfma_f32_16x16x32_bf16 v[8:11], v[116:119], v[92:95], v[8:11]
	v_mfma_f32_16x16x32_bf16 v[0:3], v[120:123], v[92:95], v[0:3]
	ds_read_b128 v[88:91], v110
	ds_read_b128 v[92:95], v110 offset:2048
	ds_read_b128 v[116:119], v111 offset:20480
	ds_read_b128 v[120:123], v111 offset:22528
	s_waitcnt lgkmcnt(3)
	v_mfma_f32_16x16x32_bf16 v[60:63], v[80:83], v[88:91], v[60:63]
	v_mfma_f32_16x16x32_bf16 v[56:59], v[84:87], v[88:91], v[56:59]
	s_waitcnt lgkmcnt(1)
	v_mfma_f32_16x16x32_bf16 v[52:55], v[116:119], v[88:91], v[52:55]
	s_waitcnt lgkmcnt(0)
	v_mfma_f32_16x16x32_bf16 v[48:51], v[120:123], v[88:91], v[48:51]
	ds_read_b128 v[88:91], v110 offset:4096
	ds_read_b128 v[144:147], v110 offset:6144
	v_mfma_f32_16x16x32_bf16 v[44:47], v[80:83], v[92:95], v[44:47]
	v_mfma_f32_16x16x32_bf16 v[40:43], v[84:87], v[92:95], v[40:43]
	v_mfma_f32_16x16x32_bf16 v[36:39], v[116:119], v[92:95], v[36:39]
	v_mfma_f32_16x16x32_bf16 v[32:35], v[120:123], v[92:95], v[32:35]
	s_waitcnt lgkmcnt(1)
	v_mfma_f32_16x16x32_bf16 v[28:31], v[80:83], v[88:91], v[28:31]
	v_mfma_f32_16x16x32_bf16 v[24:27], v[84:87], v[88:91], v[24:27]
	v_mfma_f32_16x16x32_bf16 v[20:23], v[116:119], v[88:91], v[20:23]
	v_mfma_f32_16x16x32_bf16 v[16:19], v[120:123], v[88:91], v[16:19]
	s_waitcnt lgkmcnt(0)
	v_mfma_f32_16x16x32_bf16 v[4:7], v[80:83], v[144:147], v[4:7]
	v_mfma_f32_16x16x32_bf16 v[12:15], v[84:87], v[144:147], v[12:15]
	v_mfma_f32_16x16x32_bf16 v[8:11], v[116:119], v[144:147], v[8:11]
	v_mfma_f32_16x16x32_bf16 v[0:3], v[120:123], v[144:147], v[0:3]
	s_setprio 0
	s_cmp_eq_u32 s1, 17
	s_cbranch_scc0 .LBB0_71
; __device__ __forceinline__ unsigned pk_bf16(float lo, float hi) { unsigned r; asm("v_cvt_pk_bf16_f32 %0, %1, %2" : "=v"(r) : "v"(lo), "v"(hi)); return r; }
;     __device__ __forceinline__ void operator()(const f32x4 (&acc)[4][4], int tm, int tn, int wr, int wc, int fr, int fq, const float*) const {
;         const int col0 = tn * 128 + wc * 64 + fq * 16;
; #pragma unroll
;         for (int m = 0; m < 4; ++m) {
;             const size_t row = (size_t)tm * 128 + wr * 64 + m * 16 + fr;
;             f32x4 o[4]; float sq = 0.f;
; #pragma unroll
;             for (int n = 0; n < 4; ++n) {
;                 o[n] = *(const f32x4*)(xin + row * 1024 + col0 + n * 4) + acc[m][n];
;                 *(f32x4*)(xout + row * 1024 + col0 + n * 4) = o[n];
;                 sq += o[n][0] * o[n][0] + o[n][1] * o[n][1] + o[n][2] * o[n][2] + o[n][3] * o[n][3];
;             }
;             u32x4 w0, w1;
;             w0.x = pk_bf16(o[0][0], o[0][1]); w0.y = pk_bf16(o[0][2], o[0][3]); w0.z = pk_bf16(o[1][0], o[1][1]); w0.w = pk_bf16(o[1][2], o[1][3]);
;             w1.x = pk_bf16(o[2][0], o[2][1]); w1.y = pk_bf16(o[2][2], o[2][3]); w1.z = pk_bf16(o[3][0], o[3][1]); w1.w = pk_bf16(o[3][2], o[3][3]);
;             *(u32x4*)(xb + row * 1024 + col0) = w0; *(u32x4*)(xb + row * 1024 + col0 + 8) = w1;
;             sq += __shfl_xor(sq, 16); sq += __shfl_xor(sq, 32);
;             if (fq == 0) ssq[(size_t)(tn * 2 + wc) * T + row] = sq;
;         }
	s_mov_b32 s21, 0
	s_movk_i32 s20, 0x780
	s_mov_b32 s13, 15
	v_lshlrev_b32_e32 v66, 6, v99
	s_lshl_b32 s20, s12, 7
	v_ashrrev_i32_e32 v67, 31, v66
	s_lshl_b32 s1, s0, 7
	v_lshlrev_b32_e32 v64, 6, v96
	v_lshlrev_b32_e32 v65, 4, v97
	v_lshl_add_u64 v[66:67], s[20:21], 0, v[66:67]
	v_or3_b32 v64, v64, s1, v65
	v_or_b32_e32 v66, v66, v98
	v_lshl_or_b32 v68, s0, 1, v96
	v_ashrrev_i32_e32 v65, 31, v64
	v_ashrrev_i32_e32 v69, 31, v68
	v_lshlrev_b64 v[76:77], 12, v[66:67]
	v_lshlrev_b64 v[70:71], 17, v[68:69]
	v_lshl_add_u64 v[72:73], s[22:23], 0, v[76:77]
	v_lshlrev_b64 v[68:69], 2, v[64:65]
	v_lshl_add_u64 v[78:79], v[72:73], 0, v[68:69]
	global_load_dwordx4 v[82:85], v[78:79], off
	global_load_dwordx4 v[86:89], v[78:79], off offset:16
	global_load_dwordx4 v[90:93], v[78:79], off offset:32
	global_load_dwordx4 v[116:119], v[78:79], off offset:48
	v_add_co_u32_e32 v94, vcc, 0x10000, v78
	s_nop 1
	v_addc_co_u32_e32 v95, vcc, 0, v79, vcc
	global_load_dwordx4 v[120:123], v[94:95], off
	global_load_dwordx4 v[144:147], v[94:95], off offset:16
	global_load_dwordx4 v[148:151], v[94:95], off offset:32
	global_load_dwordx4 v[152:155], v[94:95], off offset:48
	v_add_co_u32_e32 v94, vcc, 0x20000, v78
	s_nop 1
	v_addc_co_u32_e32 v95, vcc, 0, v79, vcc
	global_load_dwordx4 v[156:159], v[94:95], off
	global_load_dwordx4 v[160:163], v[94:95], off offset:16
	global_load_dwordx4 v[100:103], v[94:95], off offset:32
	global_load_dwordx4 v[104:107], v[94:95], off offset:48
	v_add_co_u32_e32 v94, vcc, 0x30000, v78
	s_nop 1
	v_addc_co_u32_e32 v95, vcc, 0, v79, vcc
	global_load_dwordx4 v[108:111], v[94:95], off
	global_load_dwordx4 v[136:139], v[94:95], off offset:16
	global_load_dwordx4 v[140:143], v[94:95], off offset:32
	global_load_dwordx4 v[112:115], v[94:95], off offset:48
	v_readlane_b32 s36, v165, 42
	v_readlane_b32 s46, v165, 52
	v_readlane_b32 s47, v165, 53
	v_cmp_lt_i32_e64 s[0:1], v134, v132
	v_readlane_b32 s50, v165, 56
	v_readlane_b32 s51, v165, 57
	v_cmp_eq_u32_e32 vcc, 0, v97
	v_readlane_b32 s37, v165, 43
	v_readlane_b32 s38, v165, 44
	v_readlane_b32 s39, v165, 45
	v_readlane_b32 s40, v165, 46
	v_readlane_b32 s41, v165, 47
	v_readlane_b32 s42, v165, 48
	v_readlane_b32 s43, v165, 49
	v_readlane_b32 s44, v165, 50
	v_readlane_b32 s45, v165, 51
	v_readlane_b32 s48, v165, 54
	v_readlane_b32 s49, v165, 55
	s_waitcnt vmcnt(0)
	v_pk_add_f32 v[60:61], v[60:61], v[82:83]
	v_lshl_add_u64 v[72:73], s[82:83], 0, v[76:77]
	v_pk_add_f32 v[62:63], v[62:63], v[84:85]
	v_lshl_add_u64 v[76:77], v[72:73], 0, v[68:69]
	global_store_dwordx4 v[76:77], v[60:63], off
	v_mul_f32_e32 v80, v61, v61
	v_fmac_f32_e32 v80, v60, v60
	v_fmac_f32_e32 v80, v62, v62
	v_fmac_f32_e32 v80, v63, v63
	v_cvt_pk_bf16_f32 v60, v60, v61
	v_cvt_pk_bf16_f32 v61, v62, v63
	v_pk_add_f32 v[56:57], v[56:57], v[86:87]
	s_nop 0
	v_mul_f32_e32 v72, v57, v57
	v_pk_add_f32 v[58:59], v[58:59], v[88:89]
	v_fmac_f32_e32 v72, v56, v56
	v_fmac_f32_e32 v72, v58, v58
	global_store_dwordx4 v[76:77], v[56:59], off offset:16
	v_fmac_f32_e32 v72, v59, v59
	v_add_f32_e32 v80, v80, v72
	v_cvt_pk_bf16_f32 v62, v56, v57
	v_cvt_pk_bf16_f32 v63, v58, v59
	v_pk_add_f32 v[52:53], v[52:53], v[90:91]
	s_nop 0
	v_mul_f32_e32 v72, v53, v53
	v_pk_add_f32 v[54:55], v[54:55], v[92:93]
	v_fmac_f32_e32 v72, v52, v52
	v_fmac_f32_e32 v72, v54, v54
	global_store_dwordx4 v[76:77], v[52:55], off offset:32
	v_fmac_f32_e32 v72, v55, v55
	v_add_f32_e32 v80, v80, v72
	v_cvt_pk_bf16_f32 v52, v52, v53
	v_cvt_pk_bf16_f32 v53, v54, v55
	v_pk_add_f32 v[48:49], v[48:49], v[116:117]
	v_pk_add_f32 v[50:51], v[50:51], v[118:119]
	v_mul_f32_e32 v72, v49, v49
	global_store_dwordx4 v[76:77], v[48:51], off offset:48
	v_fmac_f32_e32 v72, v48, v48
	v_cvt_pk_bf16_f32 v54, v48, v49
	v_fmac_f32_e32 v72, v50, v50
	v_lshlrev_b64 v[48:49], 11, v[66:67]
	v_lshl_add_u64 v[48:49], s[46:47], 0, v[48:49]
	v_lshl_add_u64 v[48:49], v[64:65], 1, v[48:49]
	v_fmac_f32_e32 v72, v51, v51
	v_cvt_pk_bf16_f32 v55, v50, v51
	global_store_dwordx4 v[48:49], v[60:63], off
	global_store_dwordx4 v[48:49], v[52:55], off offset:16
	v_cndmask_b32_e64 v48, v130, v134, s[0:1]
	v_add_f32_e32 v72, v80, v72
	v_lshlrev_b32_e32 v50, 2, v48
	ds_bpermute_b32 v48, v50, v72
	v_cmp_lt_i32_e64 s[0:1], v133, v132
	s_waitcnt lgkmcnt(0)
	v_add_f32_e32 v52, v72, v48
	v_cndmask_b32_e64 v48, v130, v133, s[0:1]
	v_lshlrev_b32_e32 v51, 2, v48
	ds_bpermute_b32 v53, v51, v52
	v_lshl_add_u64 v[48:49], s[50:51], 0, v[70:71]
	v_lshl_add_u64 v[48:49], v[66:67], 2, v[48:49]
	s_and_saveexec_b64 s[0:1], vcc
	s_cbranch_execz .LBB0_74
	s_waitcnt lgkmcnt(0)
	v_add_f32_e32 v52, v52, v53
	global_store_dword v[48:49], v52, off

; template <class Epi>
; __device__ __forceinline__ void gemm_tile64(const bf16_t* A, const bf16_t* Bt, int tm, int tn, const Epi& epi, char* smem, const float* ssq, int nparts) {
;     ...
;         for (int ks = 0; ks < 2; ++ks) {
;             bf16x8 af[4], bfr[4];
; #pragma unroll
;             for (int m = 0; m < 4; ++m) { const int r = wr * 64 + m * 16 + fr; af[m] = *(const bf16x8*)(sA + r * 64 + (((ks * 4 + fq) ^ ((r >> 1) & 7)) * 8)); }
; #pragma unroll
;             for (int n = 0; n < 4; ++n) { const int r = wc * 64 + n * 16 + fr; bfr[n] = *(const bf16x8*)(sB + r * 64 + (((ks * 4 + fq) ^ ((r >> 1) & 7)) * 8)); }
; #pragma unroll
;             for (int m = 0; m < 4; ++m)
; #pragma unroll
;                 for (int n = 0; n < 4; ++n) acc[m][n] = __builtin_amdgcn_mfma_f32_16x16x32_bf16(bfr[n], af[m], acc[m][n], 0, 0, 0);
;     __device__ __forceinline__ void operator()(const f32x4 (&acc)[4][4], int tm, int tn, int wr, int wc, int fr, int fq, const float* sRs) const {
;         const int col0 = tn * 128 + wc * 64 + fq * 16;
; #pragma unroll
;         for (int m = 0; m < 4; ++m) {
;             const int rl = wr * 64 + m * 16 + fr; const float rs = sRs[rl]; const size_t row = (size_t)tm * 128 + rl;
.Lgi_nopf:
	s_setprio 2
	s_waitcnt lgkmcnt(3)
	v_mfma_f32_16x16x32_bf16 v[60:63], v[80:83], v[88:91], v[60:63]
	v_mfma_f32_16x16x32_bf16 v[56:59], v[84:87], v[88:91], v[56:59]
	s_waitcnt lgkmcnt(1)
	v_mfma_f32_16x16x32_bf16 v[52:55], v[116:119], v[88:91], v[52:55]
	s_waitcnt lgkmcnt(0)
	v_mfma_f32_16x16x32_bf16 v[48:51], v[120:123], v[88:91], v[48:51]
	v_mfma_f32_16x16x32_bf16 v[44:47], v[80:83], v[92:95], v[44:47]
	v_mfma_f32_16x16x32_bf16 v[40:43], v[84:87], v[92:95], v[40:43]
	v_mfma_f32_16x16x32_bf16 v[36:39], v[116:119], v[92:95], v[36:39]
	v_mfma_f32_16x16x32_bf16 v[32:35], v[120:123], v[92:95], v[32:35]
	ds_read_b128 v[88:91], v108 offset:4096
	ds_read_b128 v[92:95], v108 offset:6144
	s_waitcnt lgkmcnt(1)
	v_mfma_f32_16x16x32_bf16 v[28:31], v[80:83], v[88:91], v[28:31]
	v_mfma_f32_16x16x32_bf16 v[24:27], v[84:87], v[88:91], v[24:27]
	v_mfma_f32_16x16x32_bf16 v[16:19], v[116:119], v[88:91], v[16:19]
	v_mfma_f32_16x16x32_bf16 v[12:15], v[120:123], v[88:91], v[12:15]
	s_waitcnt lgkmcnt(0)
	v_mfma_f32_16x16x32_bf16 v[8:11], v[80:83], v[92:95], v[8:11]
	v_mfma_f32_16x16x32_bf16 v[20:23], v[84:87], v[92:95], v[20:23]
	ds_read_b128 v[80:83], v111 offset:16384
	ds_read_b128 v[84:87], v111 offset:18432
	v_mfma_f32_16x16x32_bf16 v[4:7], v[116:119], v[92:95], v[4:7]
	v_mfma_f32_16x16x32_bf16 v[0:3], v[120:123], v[92:95], v[0:3]
	ds_read_b128 v[88:91], v110
	ds_read_b128 v[92:95], v110 offset:2048
	ds_read_b128 v[116:119], v111 offset:20480
	ds_read_b128 v[120:123], v111 offset:22528
	s_waitcnt lgkmcnt(3)
	v_mfma_f32_16x16x32_bf16 v[60:63], v[80:83], v[88:91], v[60:63]
	v_mfma_f32_16x16x32_bf16 v[56:59], v[84:87], v[88:91], v[56:59]
	s_waitcnt lgkmcnt(1)
	v_mfma_f32_16x16x32_bf16 v[52:55], v[116:119], v[88:91], v[52:55]
	s_waitcnt lgkmcnt(0)
	v_mfma_f32_16x16x32_bf16 v[48:51], v[120:123], v[88:91], v[48:51]
	ds_read_b128 v[88:91], v110 offset:4096
	ds_read_b128 v[144:147], v110 offset:6144
	v_mfma_f32_16x16x32_bf16 v[44:47], v[80:83], v[92:95], v[44:47]
	v_mfma_f32_16x16x32_bf16 v[40:43], v[84:87], v[92:95], v[40:43]
	v_mfma_f32_16x16x32_bf16 v[36:39], v[116:119], v[92:95], v[36:39]
	v_mfma_f32_16x16x32_bf16 v[32:35], v[120:123], v[92:95], v[32:35]
	s_waitcnt lgkmcnt(1)
	v_mfma_f32_16x16x32_bf16 v[28:31], v[80:83], v[88:91], v[28:31]
	v_mfma_f32_16x16x32_bf16 v[24:27], v[84:87], v[88:91], v[24:27]
	v_mfma_f32_16x16x32_bf16 v[16:19], v[116:119], v[88:91], v[16:19]
	v_mfma_f32_16x16x32_bf16 v[12:15], v[120:123], v[88:91], v[12:15]
	s_waitcnt lgkmcnt(0)
	v_mfma_f32_16x16x32_bf16 v[8:11], v[80:83], v[144:147], v[8:11]
	v_mfma_f32_16x16x32_bf16 v[20:23], v[84:87], v[144:147], v[20:23]
	v_mfma_f32_16x16x32_bf16 v[4:7], v[116:119], v[144:147], v[4:7]
	v_mfma_f32_16x16x32_bf16 v[0:3], v[120:123], v[144:147], v[0:3]
	s_setprio 0
	s_cmp_eq_u32 s0, 17
	s_cbranch_scc0 .LBB0_376
	s_mov_b32 s21, 0
	s_movk_i32 s20, 0x780
	s_mov_b32 s1, 15
	s_cmp_lt_u32 s22, 8
	s_cbranch_scc0 .Lnq_skip
	v_mul_f32_e32 v64, v48, v48
	v_fmac_f32_e32 v64, v49, v49
	v_fmac_f32_e32 v64, v50, v50
	v_fmac_f32_e32 v64, v51, v51
	v_fmac_f32_e32 v64, v52, v52
	v_fmac_f32_e32 v64, v53, v53
	v_fmac_f32_e32 v64, v54, v54
	v_fmac_f32_e32 v64, v55, v55
	v_fmac_f32_e32 v64, v56, v56
	v_fmac_f32_e32 v64, v57, v57
	v_fmac_f32_e32 v64, v58, v58
	v_fmac_f32_e32 v64, v59, v59
	v_fmac_f32_e32 v64, v60, v60
	v_fmac_f32_e32 v64, v61, v61
	v_fmac_f32_e32 v64, v62, v62
	v_fmac_f32_e32 v64, v63, v63
	v_mul_f32_e32 v65, v32, v32
	v_fmac_f32_e32 v65, v33, v33
	v_fmac_f32_e32 v65, v34, v34
	v_fmac_f32_e32 v65, v35, v35
	v_fmac_f32_e32 v65, v36, v36
	v_fmac_f32_e32 v65, v37, v37
	v_fmac_f32_e32 v65, v38, v38
	v_fmac_f32_e32 v65, v39, v39
	v_fmac_f32_e32 v65, v40, v40
	v_fmac_f32_e32 v65, v41, v41
	v_fmac_f32_e32 v65, v42, v42
	v_fmac_f32_e32 v65, v43, v43
	v_fmac_f32_e32 v65, v44, v44
	v_fmac_f32_e32 v65, v45, v45
	v_fmac_f32_e32 v65, v46, v46
	v_fmac_f32_e32 v65, v47, v47
	v_mul_f32_e32 v66, v12, v12
	v_fmac_f32_e32 v66, v13, v13
	v_fmac_f32_e32 v66, v14, v14
	v_fmac_f32_e32 v66, v15, v15
	v_fmac_f32_e32 v66, v16, v16
	v_fmac_f32_e32 v66, v17, v17
	v_fmac_f32_e32 v66, v18, v18
	v_fmac_f32_e32 v66, v19, v19
	v_fmac_f32_e32 v66, v24, v24
	v_fmac_f32_e32 v66, v25, v25
	v_fmac_f32_e32 v66, v26, v26
	v_fmac_f32_e32 v66, v27, v27
	v_fmac_f32_e32 v66, v28, v28
	v_fmac_f32_e32 v66, v29, v29
	v_fmac_f32_e32 v66, v30, v30
	v_fmac_f32_e32 v66, v31, v31
	v_mul_f32_e32 v67, v0, v0
	v_fmac_f32_e32 v67, v1, v1
	v_fmac_f32_e32 v67, v2, v2
	v_fmac_f32_e32 v67, v3, v3
	v_fmac_f32_e32 v67, v4, v4
	v_fmac_f32_e32 v67, v5, v5
	v_fmac_f32_e32 v67, v6, v6
	v_fmac_f32_e32 v67, v7, v7
	v_fmac_f32_e32 v67, v8, v8
	v_fmac_f32_e32 v67, v9, v9
	v_fmac_f32_e32 v67, v10, v10
	v_fmac_f32_e32 v67, v11, v11
	v_fmac_f32_e32 v67, v20, v20
	v_fmac_f32_e32 v67, v21, v21
	v_fmac_f32_e32 v67, v22, v22
	v_fmac_f32_e32 v67, v23, v23
	v_mov_b32_e32 v68, v64
	s_nop 1
	v_permlane16_swap_b32_e32 v68, v64
	v_add_f32_e32 v64, v64, v68
	v_mov_b32_e32 v68, v64
	s_nop 1
	v_permlane32_swap_b32_e32 v68, v64
	v_add_f32_e32 v64, v64, v68
	v_mov_b32_e32 v68, v65
	s_nop 1
	v_permlane16_swap_b32_e32 v68, v65
	v_add_f32_e32 v65, v65, v68
	v_mov_b32_e32 v68, v65
	s_nop 1
	v_permlane32_swap_b32_e32 v68, v65
	v_add_f32_e32 v65, v65, v68
	v_mov_b32_e32 v68, v66
	s_nop 1
	v_permlane16_swap_b32_e32 v68, v66
	v_add_f32_e32 v66, v66, v68
	v_mov_b32_e32 v68, v66
	s_nop 1
	v_permlane32_swap_b32_e32 v68, v66
	v_add_f32_e32 v66, v66, v68
	v_mov_b32_e32 v68, v67
	s_nop 1
	v_permlane16_swap_b32_e32 v68, v67
	v_add_f32_e32 v67, v67, v68
	v_mov_b32_e32 v68, v67
	s_nop 1
	v_permlane32_swap_b32_e32 v68, v67
	v_add_f32_e32 v67, v67, v68
	v_lshl_or_b32 v69, v96, 6, v98
	v_lshlrev_b32_e32 v69, 2, v69
	ds_read_b32 v70, v69 offset:32768
	ds_read_b32 v71, v69 offset:32832
	ds_read_b32 v72, v69 offset:32896
	ds_read_b32 v73, v69 offset:32960
	v_readlane_b32 s98, v165, 2
	v_readlane_b32 s99, v165, 3
	v_readlane_b32 s32, v167, 36
	s_waitcnt lgkmcnt(0)
	v_mul_f32_e32 v70, v70, v70
	v_mul_f32_e32 v64, v64, v70
	v_mul_f32_e32 v71, v71, v71
	v_mul_f32_e32 v65, v65, v71
	v_mul_f32_e32 v72, v72, v72
	v_mul_f32_e32 v66, v66, v72
	v_mul_f32_e32 v73, v73, v73
	v_mul_f32_e32 v67, v67, v73
	v_max3_f32 v64, v64, v65, v66
	v_max_f32_e32 v64, v64, v67
	s_mul_i32 s32, s32, 0xc00
	s_add_i32 s32, s32, 32
	v_mov_b32_e32 v69, s32
	s_and_b32 s32, s2, 7
	v_lshl_add_u32 v69, s32, 7, v69
	v_max_f32_dpp v64, v64, v64 row_ror:8 row_mask:0xf bank_mask:0xf
	s_lshr_b32 s32, s22, 2
	v_lshl_add_u32 v69, s32, 10, v69
	v_max_f32_dpp v64, v64, v64 row_ror:4 row_mask:0xf bank_mask:0xf
	s_and_b32 s32, s22, 3
	v_lshl_add_u32 v69, s32, 3, v69
	v_max_f32_dpp v64, v64, v64 quad_perm:[2,3,0,1] row_mask:0xf bank_mask:0xf
	v_lshl_add_u32 v69, v97, 2, v69
	v_cmp_eq_u32_e32 vcc, 0, v130
	v_max_f32_dpp v64, v64, v64 quad_perm:[1,0,3,2] row_mask:0xf bank_mask:0xf
	s_and_saveexec_b64 s[36:37], vcc
	global_atomic_umax v69, v64, s[98:99]
	s_or_b64 exec, exec, s[36:37]
